# differential attention rescale blocks: 64 v_mul_f32 per block replaced by 32 v_pk_mul_f32 with a broadcast factor (IEEE-identical), 4 bodies (on v109)
# speedup vs baseline: 1.0054x; 1.0054x over previous
.LBB0_331:
	v_add_f32_e32 v7, v7, v6
	v_mov_b32_e32 v8, v7
	s_nop 1
	v_permlane32_swap_b32_e32 v7, v8
	v_max_f32_e32 v8, v8, v8
	v_max_f32_e32 v7, v7, v8
	v_add_f32_e32 v8, 0x42000000, v246
	v_cmp_gt_f32_e32 vcc, v7, v8
	s_cbranch_vccz .LBB0_333
	v_max_f32_e32 v7, v7, v7
	v_max_f32_e32 v8, v246, v246
	v_max_f32_e32 v7, v8, v7
	v_sub_f32_e32 v8, v246, v7
	v_exp_f32_e32 v8, v8
	v_mov_b32_e32 v246, v7
	v_pk_mul_f32 v[64:65], v[64:65], v[8:9] op_sel_hi:[1,0]
	v_pk_mul_f32 v[66:67], v[66:67], v[8:9] op_sel_hi:[1,0]
	v_pk_mul_f32 v[68:69], v[68:69], v[8:9] op_sel_hi:[1,0]
	v_pk_mul_f32 v[70:71], v[70:71], v[8:9] op_sel_hi:[1,0]
	v_pk_mul_f32 v[72:73], v[72:73], v[8:9] op_sel_hi:[1,0]
	v_pk_mul_f32 v[74:75], v[74:75], v[8:9] op_sel_hi:[1,0]
	v_pk_mul_f32 v[76:77], v[76:77], v[8:9] op_sel_hi:[1,0]
	v_pk_mul_f32 v[78:79], v[78:79], v[8:9] op_sel_hi:[1,0]
	v_pk_mul_f32 v[48:49], v[48:49], v[8:9] op_sel_hi:[1,0]
	v_pk_mul_f32 v[50:51], v[50:51], v[8:9] op_sel_hi:[1,0]
	v_pk_mul_f32 v[52:53], v[52:53], v[8:9] op_sel_hi:[1,0]
	v_pk_mul_f32 v[54:55], v[54:55], v[8:9] op_sel_hi:[1,0]
	v_pk_mul_f32 v[56:57], v[56:57], v[8:9] op_sel_hi:[1,0]
	v_pk_mul_f32 v[58:59], v[58:59], v[8:9] op_sel_hi:[1,0]
	v_pk_mul_f32 v[60:61], v[60:61], v[8:9] op_sel_hi:[1,0]
	v_pk_mul_f32 v[62:63], v[62:63], v[8:9] op_sel_hi:[1,0]
	v_pk_mul_f32 v[32:33], v[32:33], v[8:9] op_sel_hi:[1,0]
	v_pk_mul_f32 v[34:35], v[34:35], v[8:9] op_sel_hi:[1,0]
	v_pk_mul_f32 v[36:37], v[36:37], v[8:9] op_sel_hi:[1,0]
	v_pk_mul_f32 v[38:39], v[38:39], v[8:9] op_sel_hi:[1,0]
	v_pk_mul_f32 v[40:41], v[40:41], v[8:9] op_sel_hi:[1,0]
	v_pk_mul_f32 v[42:43], v[42:43], v[8:9] op_sel_hi:[1,0]
	v_pk_mul_f32 v[44:45], v[44:45], v[8:9] op_sel_hi:[1,0]
	v_pk_mul_f32 v[46:47], v[46:47], v[8:9] op_sel_hi:[1,0]
	v_pk_mul_f32 v[16:17], v[16:17], v[8:9] op_sel_hi:[1,0]
	v_pk_mul_f32 v[18:19], v[18:19], v[8:9] op_sel_hi:[1,0]
	v_pk_mul_f32 v[20:21], v[20:21], v[8:9] op_sel_hi:[1,0]
	v_pk_mul_f32 v[22:23], v[22:23], v[8:9] op_sel_hi:[1,0]
	v_pk_mul_f32 v[24:25], v[24:25], v[8:9] op_sel_hi:[1,0]
	v_pk_mul_f32 v[26:27], v[26:27], v[8:9] op_sel_hi:[1,0]
	v_pk_mul_f32 v[28:29], v[28:29], v[8:9] op_sel_hi:[1,0]
	v_pk_mul_f32 v[30:31], v[30:31], v[8:9] op_sel_hi:[1,0]
	v_mul_f32_e32 v245, v245, v8

.LBB0_400:
	v_add_f32_e32 v2, v4, v3
	v_mov_b32_e32 v4, v2
	s_nop 1
	v_permlane32_swap_b32_e32 v2, v4
	v_max_f32_e32 v4, v4, v4
	v_max_f32_e32 v2, v2, v4
	v_add_f32_e32 v4, 0x42000000, v246
	v_cmp_gt_f32_e32 vcc, v2, v4
	s_cbranch_vccz .LBB0_402
	v_max_f32_e32 v2, v2, v2
	v_max_f32_e32 v4, v246, v246
	v_max_f32_e32 v2, v4, v2
	v_sub_f32_e32 v4, v246, v2
	v_exp_f32_e32 v4, v4
	v_mov_b32_e32 v246, v2
	v_pk_mul_f32 v[64:65], v[64:65], v[4:5] op_sel_hi:[1,0]
	v_pk_mul_f32 v[66:67], v[66:67], v[4:5] op_sel_hi:[1,0]
	v_pk_mul_f32 v[68:69], v[68:69], v[4:5] op_sel_hi:[1,0]
	v_pk_mul_f32 v[70:71], v[70:71], v[4:5] op_sel_hi:[1,0]
	v_pk_mul_f32 v[72:73], v[72:73], v[4:5] op_sel_hi:[1,0]
	v_pk_mul_f32 v[74:75], v[74:75], v[4:5] op_sel_hi:[1,0]
	v_pk_mul_f32 v[76:77], v[76:77], v[4:5] op_sel_hi:[1,0]
	v_pk_mul_f32 v[78:79], v[78:79], v[4:5] op_sel_hi:[1,0]
	v_pk_mul_f32 v[48:49], v[48:49], v[4:5] op_sel_hi:[1,0]
	v_pk_mul_f32 v[50:51], v[50:51], v[4:5] op_sel_hi:[1,0]
	v_pk_mul_f32 v[52:53], v[52:53], v[4:5] op_sel_hi:[1,0]
	v_pk_mul_f32 v[54:55], v[54:55], v[4:5] op_sel_hi:[1,0]
	v_pk_mul_f32 v[56:57], v[56:57], v[4:5] op_sel_hi:[1,0]
	v_pk_mul_f32 v[58:59], v[58:59], v[4:5] op_sel_hi:[1,0]
	v_pk_mul_f32 v[60:61], v[60:61], v[4:5] op_sel_hi:[1,0]
	v_pk_mul_f32 v[62:63], v[62:63], v[4:5] op_sel_hi:[1,0]
	v_pk_mul_f32 v[32:33], v[32:33], v[4:5] op_sel_hi:[1,0]
	v_pk_mul_f32 v[34:35], v[34:35], v[4:5] op_sel_hi:[1,0]
	v_pk_mul_f32 v[36:37], v[36:37], v[4:5] op_sel_hi:[1,0]
	v_pk_mul_f32 v[38:39], v[38:39], v[4:5] op_sel_hi:[1,0]
	v_pk_mul_f32 v[40:41], v[40:41], v[4:5] op_sel_hi:[1,0]
	v_pk_mul_f32 v[42:43], v[42:43], v[4:5] op_sel_hi:[1,0]
	v_pk_mul_f32 v[44:45], v[44:45], v[4:5] op_sel_hi:[1,0]
	v_pk_mul_f32 v[46:47], v[46:47], v[4:5] op_sel_hi:[1,0]
	v_pk_mul_f32 v[16:17], v[16:17], v[4:5] op_sel_hi:[1,0]
	v_pk_mul_f32 v[18:19], v[18:19], v[4:5] op_sel_hi:[1,0]
	v_pk_mul_f32 v[20:21], v[20:21], v[4:5] op_sel_hi:[1,0]
	v_pk_mul_f32 v[22:23], v[22:23], v[4:5] op_sel_hi:[1,0]
	v_pk_mul_f32 v[24:25], v[24:25], v[4:5] op_sel_hi:[1,0]
	v_pk_mul_f32 v[26:27], v[26:27], v[4:5] op_sel_hi:[1,0]
	v_pk_mul_f32 v[28:29], v[28:29], v[4:5] op_sel_hi:[1,0]
	v_pk_mul_f32 v[30:31], v[30:31], v[4:5] op_sel_hi:[1,0]
	v_mul_f32_e32 v245, v245, v4
